# g4_epilogue_base_prefetch
# baseline (speedup 1.0000x reference)
; __device__ __forceinline__ unsigned pk2(float lo, float hi) { const f32x2_t v = {lo, hi}; const bf16x2_t b = __builtin_convertvector(v, bf16x2_t); return __builtin_bit_cast(unsigned, b); }
; __device__ __forceinline__ float bperm_f(int src_lane, float v) { return __builtin_bit_cast(float, __builtin_amdgcn_ds_bpermute(src_lane << 2, __builtin_bit_cast(int, v))); }
;     __device__ __forceinline__ void operator()(Acc& acc, const Unit& u, int wr, int wc, int fr, int fq) const {
;     ...
;                 u32x4 raw[2][2];
; #pragma unroll
;                 for (int mm = 0; mm < 2; ++mm)
; #pragma unroll
;                     for (int bj = 0; bj < 2; ++bj) raw[mm][bj] = *(const u32x4*)(xb + (size_t)(row0 + ai * 128 + (2 * mh + mm) * 16) * DM + col0 + bj * 128);
; #pragma unroll
;                 for (int mm = 0; mm < 2; ++mm)
; #pragma unroll
;                     for (int bj = 0; bj < 2; ++bj) { float t[8]; unpack8(raw[mm][bj], t); b0[mm][bj] = (f32x4){t[0], t[1], t[2], t[3]}; b1[mm][bj] = (f32x4){t[4], t[5], t[6], t[7]}; }
;             }
; #pragma unroll
;             for (int mm = 0; mm < 2; ++mm) { const int m = 2 * mh + mm;
;                 const int row = row0 + ai * 128 + m * 16; float ss = 0.f;
; #pragma unroll
;                 for (int bj = 0; bj < 2; ++bj) { const size_t off = (size_t)row * DM + col0 + bj * 128;
;                     const f32x4 v0 = acc[ai][bj][m][0] + b0[mm][bj], v1 = acc[ai][bj][m][1] + b1[mm][bj];
;                     u32x4 w; w.x = pk2(v0[0], v0[1]); w.y = pk2(v0[2], v0[3]); w.z = pk2(v1[0], v1[1]); w.w = pk2(v1[2], v1[3]);
;                     *(u32x4*)(xb + off) = w;
;                     ss += (v0[0] * v0[0] + v0[1] * v0[1]) + (v0[2] * v0[2] + v0[3] * v0[3]) + (v1[0] * v1[0] + v1[1] * v1[1]) + (v1[2] * v1[2] + v1[3] * v1[3]); }
;                 ss += bperm_f(ln ^ 16, ss); ss += bperm_f(ln ^ 32, ss);
;                 if (fq == 0) ssq[(size_t)row * 16 + u.pn * 4 + wc] = ss;
.LBB0_89:
	v_lshl_or_b32 v150, s24, 8, v161
	v_lshl_add_u32 v152, s60, 8, v2
	v_ashrrev_i32_e32 v151, 31, v150
	v_lshlrev_b64 v[182:183], 1, v[150:151]
	v_ashrrev_i32_e32 v153, 31, v152
	v_lshl_add_u64 v[154:155], s[18:19], 0, v[182:183]
	v_lshlrev_b64 v[184:185], 11, v[152:153]
	v_lshl_add_u64 v[132:133], v[154:155], 0, v[184:185]
	global_load_dwordx4 v[174:177], v[132:133], off
	global_load_dwordx4 v[178:181], v[132:133], off offset:256
	v_or_b32_e32 v156, 16, v152
	v_ashrrev_i32_e32 v157, 31, v156
	v_lshlrev_b64 v[158:159], 11, v[156:157]
	v_lshl_add_u64 v[132:133], v[154:155], 0, v[158:159]
	global_load_dwordx4 v[136:139], v[132:133], off
	s_nop 0
	global_load_dwordx4 v[132:135], v[132:133], off offset:256
	v_add_u32_e32 v198, 0x20, v152
	v_ashrrev_i32_e32 v199, 31, v198
	v_lshlrev_b64 v[198:199], 11, v[198:199]
	v_lshl_add_u64 v[198:199], v[154:155], 0, v[198:199]
	global_load_dwordx4 v[222:225], v[198:199], off
	global_load_dwordx4 v[226:229], v[198:199], off offset:256
	v_add_u32_e32 v198, 0x30, v152
	v_ashrrev_i32_e32 v199, 31, v198
	v_lshlrev_b64 v[198:199], 11, v[198:199]
	v_lshl_add_u64 v[198:199], v[154:155], 0, v[198:199]
	global_load_dwordx4 v[230:233], v[198:199], off
	global_load_dwordx4 v[234:237], v[198:199], off offset:256
	v_add_u32_e32 v198, 0x80, v152
	v_ashrrev_i32_e32 v199, 31, v198
	v_lshlrev_b64 v[198:199], 11, v[198:199]
	v_lshl_add_u64 v[198:199], v[154:155], 0, v[198:199]
	global_load_dwordx4 v[238:241], v[198:199], off
	global_load_dwordx4 v[242:245], v[198:199], off offset:256
	v_add_u32_e32 v198, 0x90, v152
	v_ashrrev_i32_e32 v199, 31, v198
	v_lshlrev_b64 v[198:199], 11, v[198:199]
	v_lshl_add_u64 v[198:199], v[154:155], 0, v[198:199]
	global_load_dwordx4 v[246:249], v[198:199], off
	global_load_dwordx4 v[250:253], v[198:199], off offset:256
	s_lshl_b32 s44, s24, 2
	s_ashr_i32 s45, s44, 31
	s_waitcnt vmcnt(8) lgkmcnt(0)
	v_lshlrev_b32_e32 v186, 16, v174
	v_and_b32_e32 v187, 0xffff0000, v174
	v_lshlrev_b32_e32 v174, 16, v175
	v_and_b32_e32 v175, 0xffff0000, v175
	v_lshlrev_b32_e32 v190, 16, v178
	v_and_b32_e32 v191, 0xffff0000, v178
	v_lshlrev_b32_e32 v178, 16, v179
	v_and_b32_e32 v179, 0xffff0000, v179
	v_lshlrev_b32_e32 v188, 16, v176
	v_and_b32_e32 v189, 0xffff0000, v176
	v_lshlrev_b32_e32 v176, 16, v177
	v_and_b32_e32 v177, 0xffff0000, v177
	v_lshlrev_b32_e32 v192, 16, v180
	v_and_b32_e32 v193, 0xffff0000, v180
	v_pk_add_f32 v[130:131], v[130:131], v[174:175]
	v_pk_add_f32 v[128:129], v[128:129], v[186:187]
	v_pk_add_f32 v[122:123], v[122:123], v[178:179]
	v_pk_add_f32 v[120:121], v[120:121], v[190:191]
	v_lshlrev_b32_e32 v180, 16, v181
	v_and_b32_e32 v181, 0xffff0000, v181
	v_pk_add_f32 v[126:127], v[126:127], v[176:177]
	v_pk_add_f32 v[124:125], v[124:125], v[188:189]
	v_pk_add_f32 v[176:177], v[116:117], v[192:193]
	v_cvt_pk_bf16_f32 v116, v128, v129
	v_cvt_pk_bf16_f32 v117, v130, v131
	v_mul_f32_e32 v129, v129, v129
	v_mul_f32_e32 v131, v131, v131
	v_mul_f32_e32 v178, v121, v121
	v_mul_f32_e32 v179, v123, v123
	v_pk_add_f32 v[174:175], v[118:119], v[180:181]
	v_cvt_pk_bf16_f32 v118, v124, v125
	v_cvt_pk_bf16_f32 v119, v126, v127
	v_mul_f32_e32 v125, v125, v125
	v_mul_f32_e32 v127, v127, v127
	v_mul_f32_e32 v180, v177, v177
	v_fmac_f32_e32 v129, v128, v128
	v_fmac_f32_e32 v131, v130, v130
	v_fmac_f32_e32 v178, v120, v120
	v_fmac_f32_e32 v179, v122, v122
	v_mul_f32_e32 v181, v175, v175
	v_fmac_f32_e32 v125, v124, v124
	v_fmac_f32_e32 v127, v126, v126
	v_fmac_f32_e32 v180, v176, v176
	v_add_f32_e32 v124, v129, v131
	v_add_f32_e32 v126, v178, v179
	v_fmac_f32_e32 v181, v174, v174
	v_add_f32_e32 v124, v125, v124
	v_add_f32_e32 v125, v180, v126
	v_add_f32_e32 v124, v127, v124
	v_add_f32_e32 v125, v181, v125
	v_add_f32_e32 v126, v124, v125
	ds_bpermute_b32 v127, v162, v126
	v_lshl_add_u64 v[124:125], s[18:19], 0, v[184:185]
	v_lshl_add_u64 v[124:125], v[124:125], 0, v[182:183]
	global_store_dwordx4 v[124:125], v[116:119], off
	s_waitcnt lgkmcnt(0)
	s_nop 0
	v_add_f32_e32 v116, v126, v127
	ds_bpermute_b32 v117, v163, v116
	v_cvt_pk_bf16_f32 v118, v120, v121
	v_cvt_pk_bf16_f32 v119, v122, v123
	v_cvt_pk_bf16_f32 v120, v176, v177
	v_cvt_pk_bf16_f32 v121, v174, v175
	global_store_dwordx4 v[124:125], v[118:121], off offset:256
	s_and_saveexec_b64 s[46:47], s[40:41]
	s_cbranch_execz .LBB0_91
	v_lshlrev_b64 v[118:119], 6, v[152:153]
	v_lshl_add_u64 v[118:119], s[86:87], 0, v[118:119]
	v_lshl_add_u64 v[118:119], s[44:45], 2, v[118:119]
	s_lshl_b32 s24, s53, 2
	v_lshl_add_u64 v[118:119], v[118:119], 0, s[24:25]
	s_waitcnt lgkmcnt(0)
	v_add_f32_e32 v116, v116, v117
	global_store_dword v[118:119], v116, off
; __device__ __forceinline__ unsigned pk2(float lo, float hi) { const f32x2_t v = {lo, hi}; const bf16x2_t b = __builtin_convertvector(v, bf16x2_t); return __builtin_bit_cast(unsigned, b); }
; __device__ __forceinline__ float bperm_f(int src_lane, float v) { return __builtin_bit_cast(float, __builtin_amdgcn_ds_bpermute(src_lane << 2, __builtin_bit_cast(int, v))); }
;     __device__ __forceinline__ void operator()(Acc& acc, const Unit& u, int wr, int wc, int fr, int fq) const {
;     ...
;                     for (int bj = 0; bj < 2; ++bj) raw[mm][bj] = *(const u32x4*)(xb + (size_t)(row0 + ai * 128 + (2 * mh + mm) * 16) * DM + col0 + bj * 128);
; #pragma unroll
;                 for (int mm = 0; mm < 2; ++mm)
; #pragma unroll
;                     for (int bj = 0; bj < 2; ++bj) { float t[8]; unpack8(raw[mm][bj], t); b0[mm][bj] = (f32x4){t[0], t[1], t[2], t[3]}; b1[mm][bj] = (f32x4){t[4], t[5], t[6], t[7]}; }
;             }
; #pragma unroll
;             for (int mm = 0; mm < 2; ++mm) { const int m = 2 * mh + mm;
;                 const int row = row0 + ai * 128 + m * 16; float ss = 0.f;
; #pragma unroll
;                 for (int bj = 0; bj < 2; ++bj) { const size_t off = (size_t)row * DM + col0 + bj * 128;
;                     const f32x4 v0 = acc[ai][bj][m][0] + b0[mm][bj], v1 = acc[ai][bj][m][1] + b1[mm][bj];
;                     u32x4 w; w.x = pk2(v0[0], v0[1]); w.y = pk2(v0[2], v0[3]); w.z = pk2(v1[0], v1[1]); w.w = pk2(v1[2], v1[3]);
;                     *(u32x4*)(xb + off) = w;
;                     ss += (v0[0] * v0[0] + v0[1] * v0[1]) + (v0[2] * v0[2] + v0[3] * v0[3]) + (v1[0] * v1[0] + v1[1] * v1[1]) + (v1[2] * v1[2] + v1[3] * v1[3]); }
;                 ss += bperm_f(ln ^ 16, ss); ss += bperm_f(ln ^ 32, ss);
;                 if (fq == 0) ssq[(size_t)row * 16 + u.pn * 4 + wc] = ss;
.LBB0_91:
	s_or_b64 exec, exec, s[46:47]
	v_lshlrev_b32_e32 v116, 16, v136
	s_waitcnt lgkmcnt(0)
	v_and_b32_e32 v117, 0xffff0000, v136
	v_lshlrev_b32_e32 v118, 16, v137
	v_and_b32_e32 v119, 0xffff0000, v137
	v_lshlrev_b32_e32 v120, 16, v138
	v_and_b32_e32 v121, 0xffff0000, v138
	v_pk_add_f32 v[112:113], v[112:113], v[116:117]
	v_pk_add_f32 v[114:115], v[114:115], v[118:119]
	v_pk_add_f32 v[118:119], v[108:109], v[120:121]
	v_cvt_pk_bf16_f32 v108, v112, v113
	v_mul_f32_e32 v113, v113, v113
	v_fmac_f32_e32 v113, v112, v112
	v_mul_f32_e32 v112, v115, v115
	v_lshlrev_b32_e32 v124, 16, v132
	v_and_b32_e32 v125, 0xffff0000, v132
	v_lshlrev_b32_e32 v126, 16, v133
	v_and_b32_e32 v127, 0xffff0000, v133
	v_fmac_f32_e32 v112, v114, v114
	v_lshlrev_b32_e32 v122, 16, v139
	v_and_b32_e32 v123, 0xffff0000, v139
	v_lshlrev_b32_e32 v128, 16, v134
	v_and_b32_e32 v129, 0xffff0000, v134
	v_add_f32_e32 v112, v113, v112
	v_mul_f32_e32 v113, v119, v119
	v_pk_add_f32 v[106:107], v[106:107], v[126:127]
	v_pk_add_f32 v[104:105], v[104:105], v[124:125]
	v_pk_add_f32 v[116:117], v[110:111], v[122:123]
	v_cvt_pk_bf16_f32 v109, v114, v115
	v_fmac_f32_e32 v113, v118, v118
	v_pk_add_f32 v[114:115], v[100:101], v[128:129]
	v_mul_f32_e32 v100, v105, v105
	v_mul_f32_e32 v101, v107, v107
	v_add_f32_e32 v112, v113, v112
	v_mul_f32_e32 v113, v117, v117
	v_fmac_f32_e32 v100, v104, v104
	v_fmac_f32_e32 v101, v106, v106
	v_lshlrev_b32_e32 v130, 16, v135
	v_and_b32_e32 v131, 0xffff0000, v135
	v_fmac_f32_e32 v113, v116, v116
	v_add_f32_e32 v100, v100, v101
	v_mul_f32_e32 v101, v115, v115
	v_cvt_pk_bf16_f32 v111, v116, v117
	v_add_f32_e32 v116, v113, v112
	v_pk_add_f32 v[112:113], v[102:103], v[130:131]
	v_fmac_f32_e32 v101, v114, v114
	v_add_f32_e32 v100, v101, v100
	v_mul_f32_e32 v101, v113, v113
	v_fmac_f32_e32 v101, v112, v112
	v_add_f32_e32 v100, v101, v100
	v_add_f32_e32 v103, v116, v100
	v_cvt_pk_bf16_f32 v110, v118, v119
	ds_bpermute_b32 v118, v162, v103
	v_lshl_add_u64 v[100:101], s[18:19], 0, v[158:159]
	v_lshl_add_u64 v[116:117], v[150:151], 1, v[100:101]
	v_cvt_pk_bf16_f32 v102, v104, v105
	v_cvt_pk_bf16_f32 v104, v114, v115
	s_waitcnt lgkmcnt(0)
	v_add_f32_e32 v100, v103, v118
	ds_bpermute_b32 v101, v163, v100
	v_cvt_pk_bf16_f32 v103, v106, v107
	v_cvt_pk_bf16_f32 v105, v112, v113
	global_store_dwordx4 v[116:117], v[108:111], off
	global_store_dwordx4 v[116:117], v[102:105], off offset:256
	s_and_saveexec_b64 s[46:47], s[40:41]
	s_cbranch_execz .LBB0_93
	v_lshlrev_b64 v[102:103], 6, v[156:157]
	v_lshl_add_u64 v[102:103], s[86:87], 0, v[102:103]
	v_lshl_add_u64 v[102:103], s[44:45], 2, v[102:103]
	s_lshl_b32 s24, s53, 2
	v_lshl_add_u64 v[102:103], v[102:103], 0, s[24:25]
	s_waitcnt lgkmcnt(0)
	v_add_f32_e32 v100, v100, v101
	global_store_dword v[102:103], v100, off
.LBB0_93:
	s_or_b64 exec, exec, s[46:47]
	v_or_b32_e32 v112, 32, v152
	v_ashrrev_i32_e32 v113, 31, v112
	v_lshlrev_b64 v[122:123], 11, v[112:113]
	s_waitcnt lgkmcnt(0)
	v_lshl_add_u64 v[100:101], v[154:155], 0, v[122:123]
	s_waitcnt vmcnt(10)
	v_mov_b64_e32 v[114:115], v[222:223]
	v_mov_b64_e32 v[116:117], v[224:225]
	v_mov_b64_e32 v[118:119], v[226:227]
	v_mov_b64_e32 v[120:121], v[228:229]
	v_or_b32_e32 v108, 48, v152
	v_ashrrev_i32_e32 v109, 31, v108
	v_lshlrev_b64 v[110:111], 11, v[108:109]
	v_lshl_add_u64 v[100:101], v[154:155], 0, v[110:111]
	v_mov_b64_e32 v[104:105], v[230:231]
	v_mov_b64_e32 v[106:107], v[232:233]
	s_nop 0
	v_mov_b64_e32 v[100:101], v[234:235]
	v_mov_b64_e32 v[102:103], v[236:237]
	v_add_u32_e32 v198, 0xa0, v152
	v_ashrrev_i32_e32 v199, 31, v198
	v_lshlrev_b64 v[198:199], 11, v[198:199]
	v_lshl_add_u64 v[198:199], v[154:155], 0, v[198:199]
	global_load_dwordx4 v[222:225], v[198:199], off
	global_load_dwordx4 v[226:229], v[198:199], off offset:256
	v_add_u32_e32 v198, 0xb0, v152
	v_ashrrev_i32_e32 v199, 31, v198
	v_lshlrev_b64 v[198:199], 11, v[198:199]
	v_lshl_add_u64 v[198:199], v[154:155], 0, v[198:199]
	global_load_dwordx4 v[230:233], v[198:199], off
	global_load_dwordx4 v[234:237], v[198:199], off offset:256
	s_waitcnt lgkmcnt(0)
	v_lshlrev_b32_e32 v124, 16, v114
	v_and_b32_e32 v125, 0xffff0000, v114
	v_lshlrev_b32_e32 v114, 16, v115
	v_and_b32_e32 v115, 0xffff0000, v115
	v_lshlrev_b32_e32 v128, 16, v118
	v_and_b32_e32 v129, 0xffff0000, v118
	v_lshlrev_b32_e32 v118, 16, v119
	v_and_b32_e32 v119, 0xffff0000, v119
	v_lshlrev_b32_e32 v126, 16, v116
	v_and_b32_e32 v127, 0xffff0000, v116
	v_lshlrev_b32_e32 v116, 16, v117
	v_and_b32_e32 v117, 0xffff0000, v117
	v_lshlrev_b32_e32 v130, 16, v120
	v_and_b32_e32 v131, 0xffff0000, v120
	v_pk_add_f32 v[98:99], v[98:99], v[114:115]
	v_pk_add_f32 v[96:97], v[96:97], v[124:125]
	v_pk_add_f32 v[90:91], v[90:91], v[118:119]
	v_pk_add_f32 v[88:89], v[88:89], v[128:129]
	v_lshlrev_b32_e32 v120, 16, v121
	v_and_b32_e32 v121, 0xffff0000, v121
	v_pk_add_f32 v[94:95], v[94:95], v[116:117]
	v_pk_add_f32 v[92:93], v[92:93], v[126:127]
	v_pk_add_f32 v[116:117], v[84:85], v[130:131]
	v_cvt_pk_bf16_f32 v84, v96, v97
	v_cvt_pk_bf16_f32 v85, v98, v99
	v_mul_f32_e32 v97, v97, v97
	v_mul_f32_e32 v99, v99, v99
	v_mul_f32_e32 v118, v89, v89
	v_mul_f32_e32 v119, v91, v91
	v_pk_add_f32 v[114:115], v[86:87], v[120:121]
	v_cvt_pk_bf16_f32 v86, v92, v93
	v_cvt_pk_bf16_f32 v87, v94, v95
	v_mul_f32_e32 v93, v93, v93
	v_mul_f32_e32 v95, v95, v95
	v_mul_f32_e32 v120, v117, v117
	v_fmac_f32_e32 v97, v96, v96
	v_fmac_f32_e32 v99, v98, v98
	v_fmac_f32_e32 v118, v88, v88
	v_fmac_f32_e32 v119, v90, v90
	v_mul_f32_e32 v121, v115, v115
	v_fmac_f32_e32 v93, v92, v92
	v_fmac_f32_e32 v95, v94, v94
	v_fmac_f32_e32 v120, v116, v116
	v_add_f32_e32 v92, v97, v99
	v_add_f32_e32 v94, v118, v119
	v_fmac_f32_e32 v121, v114, v114
	v_add_f32_e32 v92, v93, v92
	v_add_f32_e32 v93, v120, v94
	v_add_f32_e32 v92, v95, v92
	v_add_f32_e32 v93, v121, v93
	v_add_f32_e32 v94, v92, v93
	ds_bpermute_b32 v95, v162, v94
	v_lshl_add_u64 v[92:93], s[18:19], 0, v[122:123]
	v_lshl_add_u64 v[92:93], v[150:151], 1, v[92:93]
	global_store_dwordx4 v[92:93], v[84:87], off
	s_waitcnt lgkmcnt(0)
	s_nop 0
	v_add_f32_e32 v84, v94, v95
	ds_bpermute_b32 v85, v163, v84
	v_cvt_pk_bf16_f32 v86, v88, v89
	v_cvt_pk_bf16_f32 v87, v90, v91
	v_cvt_pk_bf16_f32 v88, v116, v117
	v_cvt_pk_bf16_f32 v89, v114, v115
	global_store_dwordx4 v[92:93], v[86:89], off offset:256
	s_and_saveexec_b64 s[46:47], s[40:41]
	s_cbranch_execz .LBB0_95
	v_lshlrev_b64 v[86:87], 6, v[112:113]
	v_lshl_add_u64 v[86:87], s[86:87], 0, v[86:87]
	v_lshl_add_u64 v[86:87], s[44:45], 2, v[86:87]
	s_lshl_b32 s24, s53, 2
	v_lshl_add_u64 v[86:87], v[86:87], 0, s[24:25]
	s_waitcnt lgkmcnt(0)
	v_add_f32_e32 v84, v84, v85
	global_store_dword v[86:87], v84, off
; __device__ __forceinline__ unsigned pk2(float lo, float hi) { const f32x2_t v = {lo, hi}; const bf16x2_t b = __builtin_convertvector(v, bf16x2_t); return __builtin_bit_cast(unsigned, b); }
; __device__ __forceinline__ float bperm_f(int src_lane, float v) { return __builtin_bit_cast(float, __builtin_amdgcn_ds_bpermute(src_lane << 2, __builtin_bit_cast(int, v))); }
;     __device__ __forceinline__ void operator()(Acc& acc, const Unit& u, int wr, int wc, int fr, int fq) const {
;     ...
;                     for (int bj = 0; bj < 2; ++bj) raw[mm][bj] = *(const u32x4*)(xb + (size_t)(row0 + ai * 128 + (2 * mh + mm) * 16) * DM + col0 + bj * 128);
; #pragma unroll
;                 for (int mm = 0; mm < 2; ++mm)
; #pragma unroll
;                     for (int bj = 0; bj < 2; ++bj) { float t[8]; unpack8(raw[mm][bj], t); b0[mm][bj] = (f32x4){t[0], t[1], t[2], t[3]}; b1[mm][bj] = (f32x4){t[4], t[5], t[6], t[7]}; }
;             }
; #pragma unroll
;             for (int mm = 0; mm < 2; ++mm) { const int m = 2 * mh + mm;
;                 const int row = row0 + ai * 128 + m * 16; float ss = 0.f;
; #pragma unroll
;                 for (int bj = 0; bj < 2; ++bj) { const size_t off = (size_t)row * DM + col0 + bj * 128;
;                     const f32x4 v0 = acc[ai][bj][m][0] + b0[mm][bj], v1 = acc[ai][bj][m][1] + b1[mm][bj];
;                     u32x4 w; w.x = pk2(v0[0], v0[1]); w.y = pk2(v0[2], v0[3]); w.z = pk2(v1[0], v1[1]); w.w = pk2(v1[2], v1[3]);
;                     *(u32x4*)(xb + off) = w;
;                     ss += (v0[0] * v0[0] + v0[1] * v0[1]) + (v0[2] * v0[2] + v0[3] * v0[3]) + (v1[0] * v1[0] + v1[1] * v1[1]) + (v1[2] * v1[2] + v1[3] * v1[3]); }
;                 ss += bperm_f(ln ^ 16, ss); ss += bperm_f(ln ^ 32, ss);
;                 if (fq == 0) ssq[(size_t)row * 16 + u.pn * 4 + wc] = ss;
.LBB0_95:
	s_or_b64 exec, exec, s[46:47]
	v_lshlrev_b32_e32 v84, 16, v104
	s_waitcnt lgkmcnt(0)
	v_and_b32_e32 v85, 0xffff0000, v104
	v_lshlrev_b32_e32 v86, 16, v105
	v_and_b32_e32 v87, 0xffff0000, v105
	v_lshlrev_b32_e32 v88, 16, v106
	v_and_b32_e32 v89, 0xffff0000, v106
	v_pk_add_f32 v[80:81], v[80:81], v[84:85]
	v_pk_add_f32 v[82:83], v[82:83], v[86:87]
	v_pk_add_f32 v[86:87], v[76:77], v[88:89]
	v_cvt_pk_bf16_f32 v76, v80, v81
	v_mul_f32_e32 v81, v81, v81
	v_fmac_f32_e32 v81, v80, v80
	v_mul_f32_e32 v80, v83, v83
	v_lshlrev_b32_e32 v92, 16, v100
	v_and_b32_e32 v93, 0xffff0000, v100
	v_lshlrev_b32_e32 v94, 16, v101
	v_and_b32_e32 v95, 0xffff0000, v101
	v_fmac_f32_e32 v80, v82, v82
	v_lshlrev_b32_e32 v90, 16, v107
	v_and_b32_e32 v91, 0xffff0000, v107
	v_lshlrev_b32_e32 v96, 16, v102
	v_and_b32_e32 v97, 0xffff0000, v102
	v_add_f32_e32 v80, v81, v80
	v_mul_f32_e32 v81, v87, v87
	v_pk_add_f32 v[74:75], v[74:75], v[94:95]
	v_pk_add_f32 v[72:73], v[72:73], v[92:93]
	v_pk_add_f32 v[84:85], v[78:79], v[90:91]
	v_cvt_pk_bf16_f32 v77, v82, v83
	v_fmac_f32_e32 v81, v86, v86
	v_pk_add_f32 v[82:83], v[68:69], v[96:97]
	v_mul_f32_e32 v68, v73, v73
	v_mul_f32_e32 v69, v75, v75
	v_add_f32_e32 v80, v81, v80
	v_mul_f32_e32 v81, v85, v85
	v_fmac_f32_e32 v68, v72, v72
	v_fmac_f32_e32 v69, v74, v74
	v_lshlrev_b32_e32 v98, 16, v103
	v_and_b32_e32 v99, 0xffff0000, v103
	v_fmac_f32_e32 v81, v84, v84
	v_add_f32_e32 v68, v68, v69
	v_mul_f32_e32 v69, v83, v83
	v_cvt_pk_bf16_f32 v79, v84, v85
	v_add_f32_e32 v84, v81, v80
	v_pk_add_f32 v[80:81], v[70:71], v[98:99]
	v_fmac_f32_e32 v69, v82, v82
	v_add_f32_e32 v68, v69, v68
	v_mul_f32_e32 v69, v81, v81
	v_fmac_f32_e32 v69, v80, v80
	v_add_f32_e32 v68, v69, v68
	v_add_f32_e32 v71, v84, v68
	v_cvt_pk_bf16_f32 v78, v86, v87
	ds_bpermute_b32 v86, v162, v71
	v_lshl_add_u64 v[68:69], s[18:19], 0, v[110:111]
	v_lshl_add_u64 v[84:85], v[150:151], 1, v[68:69]
	v_cvt_pk_bf16_f32 v70, v72, v73
	v_cvt_pk_bf16_f32 v72, v82, v83
	s_waitcnt lgkmcnt(0)
	v_add_f32_e32 v68, v71, v86
	ds_bpermute_b32 v69, v163, v68
	v_cvt_pk_bf16_f32 v71, v74, v75
	v_cvt_pk_bf16_f32 v73, v80, v81
	global_store_dwordx4 v[84:85], v[76:79], off
	global_store_dwordx4 v[84:85], v[70:73], off offset:256
	s_and_saveexec_b64 s[46:47], s[40:41]
	s_cbranch_execz .LBB0_97
	v_lshlrev_b64 v[70:71], 6, v[108:109]
	v_lshl_add_u64 v[70:71], s[86:87], 0, v[70:71]
	v_lshl_add_u64 v[70:71], s[44:45], 2, v[70:71]
	s_lshl_b32 s24, s53, 2
	v_lshl_add_u64 v[70:71], v[70:71], 0, s[24:25]
	s_waitcnt lgkmcnt(0)
	v_add_f32_e32 v68, v68, v69
	global_store_dword v[70:71], v68, off
.LBB0_97:
	s_or_b64 exec, exec, s[46:47]
	v_add_u32_e32 v80, 0x80, v152
	v_ashrrev_i32_e32 v81, 31, v80
	v_lshlrev_b64 v[90:91], 11, v[80:81]
	s_waitcnt lgkmcnt(0)
	v_lshl_add_u64 v[68:69], v[154:155], 0, v[90:91]
	s_waitcnt vmcnt(16)
	v_mov_b64_e32 v[82:83], v[238:239]
	v_mov_b64_e32 v[84:85], v[240:241]
	v_mov_b64_e32 v[86:87], v[242:243]
	v_mov_b64_e32 v[88:89], v[244:245]
	v_add_u32_e32 v76, 0x90, v152
	v_ashrrev_i32_e32 v77, 31, v76
	v_lshlrev_b64 v[78:79], 11, v[76:77]
	v_lshl_add_u64 v[68:69], v[154:155], 0, v[78:79]
	v_mov_b64_e32 v[72:73], v[246:247]
	v_mov_b64_e32 v[74:75], v[248:249]
	s_nop 0
	v_mov_b64_e32 v[68:69], v[250:251]
	v_mov_b64_e32 v[70:71], v[252:253]
	s_waitcnt lgkmcnt(0)
	v_lshlrev_b32_e32 v92, 16, v82
	v_and_b32_e32 v93, 0xffff0000, v82
	v_lshlrev_b32_e32 v82, 16, v83
	v_and_b32_e32 v83, 0xffff0000, v83
	v_lshlrev_b32_e32 v96, 16, v86
	v_and_b32_e32 v97, 0xffff0000, v86
	v_lshlrev_b32_e32 v86, 16, v87
	v_and_b32_e32 v87, 0xffff0000, v87
	v_lshlrev_b32_e32 v94, 16, v84
	v_and_b32_e32 v95, 0xffff0000, v84
	v_lshlrev_b32_e32 v84, 16, v85
	v_and_b32_e32 v85, 0xffff0000, v85
	v_lshlrev_b32_e32 v98, 16, v88
	v_and_b32_e32 v99, 0xffff0000, v88
	v_pk_add_f32 v[66:67], v[66:67], v[82:83]
	v_pk_add_f32 v[64:65], v[64:65], v[92:93]
	v_pk_add_f32 v[58:59], v[58:59], v[86:87]
	v_pk_add_f32 v[56:57], v[56:57], v[96:97]
	v_lshlrev_b32_e32 v88, 16, v89
	v_and_b32_e32 v89, 0xffff0000, v89
	v_pk_add_f32 v[62:63], v[62:63], v[84:85]
	v_pk_add_f32 v[60:61], v[60:61], v[94:95]
	v_pk_add_f32 v[84:85], v[52:53], v[98:99]
	v_cvt_pk_bf16_f32 v52, v64, v65
	v_cvt_pk_bf16_f32 v53, v66, v67
	v_mul_f32_e32 v65, v65, v65
	v_mul_f32_e32 v67, v67, v67
	v_mul_f32_e32 v86, v57, v57
	v_mul_f32_e32 v87, v59, v59
	v_pk_add_f32 v[82:83], v[54:55], v[88:89]
	v_cvt_pk_bf16_f32 v54, v60, v61
	v_cvt_pk_bf16_f32 v55, v62, v63
	v_mul_f32_e32 v61, v61, v61
	v_mul_f32_e32 v63, v63, v63
	v_mul_f32_e32 v88, v85, v85
	v_fmac_f32_e32 v65, v64, v64
	v_fmac_f32_e32 v67, v66, v66
	v_fmac_f32_e32 v86, v56, v56
	v_fmac_f32_e32 v87, v58, v58
	v_mul_f32_e32 v89, v83, v83
	v_fmac_f32_e32 v61, v60, v60
	v_fmac_f32_e32 v63, v62, v62
	v_fmac_f32_e32 v88, v84, v84
	v_add_f32_e32 v60, v65, v67
	v_add_f32_e32 v62, v86, v87
	v_fmac_f32_e32 v89, v82, v82
	v_add_f32_e32 v60, v61, v60
	v_add_f32_e32 v61, v88, v62
	v_add_f32_e32 v60, v63, v60
	v_add_f32_e32 v61, v89, v61
	v_add_f32_e32 v62, v60, v61
	ds_bpermute_b32 v63, v162, v62
	v_lshl_add_u64 v[60:61], s[18:19], 0, v[90:91]
	v_lshl_add_u64 v[60:61], v[150:151], 1, v[60:61]
	global_store_dwordx4 v[60:61], v[52:55], off
	s_waitcnt lgkmcnt(0)
	s_nop 0
	v_add_f32_e32 v52, v62, v63
	ds_bpermute_b32 v53, v163, v52
	v_cvt_pk_bf16_f32 v54, v56, v57
	v_cvt_pk_bf16_f32 v55, v58, v59
	v_cvt_pk_bf16_f32 v56, v84, v85
	v_cvt_pk_bf16_f32 v57, v82, v83
	global_store_dwordx4 v[60:61], v[54:57], off offset:256
	s_and_saveexec_b64 s[46:47], s[40:41]
	s_cbranch_execz .LBB0_99
	v_lshlrev_b64 v[54:55], 6, v[80:81]
	v_lshl_add_u64 v[54:55], s[86:87], 0, v[54:55]
	v_lshl_add_u64 v[54:55], s[44:45], 2, v[54:55]
	s_lshl_b32 s24, s53, 2
	v_lshl_add_u64 v[54:55], v[54:55], 0, s[24:25]
	s_waitcnt lgkmcnt(0)
	v_add_f32_e32 v52, v52, v53
	global_store_dword v[54:55], v52, off
; __device__ __forceinline__ unsigned pk2(float lo, float hi) { const f32x2_t v = {lo, hi}; const bf16x2_t b = __builtin_convertvector(v, bf16x2_t); return __builtin_bit_cast(unsigned, b); }
; __device__ __forceinline__ float bperm_f(int src_lane, float v) { return __builtin_bit_cast(float, __builtin_amdgcn_ds_bpermute(src_lane << 2, __builtin_bit_cast(int, v))); }
;     __device__ __forceinline__ void operator()(Acc& acc, const Unit& u, int wr, int wc, int fr, int fq) const {
;     ...
;                     for (int bj = 0; bj < 2; ++bj) raw[mm][bj] = *(const u32x4*)(xb + (size_t)(row0 + ai * 128 + (2 * mh + mm) * 16) * DM + col0 + bj * 128);
; #pragma unroll
;                 for (int mm = 0; mm < 2; ++mm)
; #pragma unroll
;                     for (int bj = 0; bj < 2; ++bj) { float t[8]; unpack8(raw[mm][bj], t); b0[mm][bj] = (f32x4){t[0], t[1], t[2], t[3]}; b1[mm][bj] = (f32x4){t[4], t[5], t[6], t[7]}; }
;             }
; #pragma unroll
;             for (int mm = 0; mm < 2; ++mm) { const int m = 2 * mh + mm;
;                 const int row = row0 + ai * 128 + m * 16; float ss = 0.f;
; #pragma unroll
;                 for (int bj = 0; bj < 2; ++bj) { const size_t off = (size_t)row * DM + col0 + bj * 128;
;                     const f32x4 v0 = acc[ai][bj][m][0] + b0[mm][bj], v1 = acc[ai][bj][m][1] + b1[mm][bj];
;                     u32x4 w; w.x = pk2(v0[0], v0[1]); w.y = pk2(v0[2], v0[3]); w.z = pk2(v1[0], v1[1]); w.w = pk2(v1[2], v1[3]);
;                     *(u32x4*)(xb + off) = w;
;                     ss += (v0[0] * v0[0] + v0[1] * v0[1]) + (v0[2] * v0[2] + v0[3] * v0[3]) + (v1[0] * v1[0] + v1[1] * v1[1]) + (v1[2] * v1[2] + v1[3] * v1[3]); }
;                 ss += bperm_f(ln ^ 16, ss); ss += bperm_f(ln ^ 32, ss);
;                 if (fq == 0) ssq[(size_t)row * 16 + u.pn * 4 + wc] = ss;
.LBB0_99:
	s_or_b64 exec, exec, s[46:47]
	v_lshlrev_b32_e32 v52, 16, v72
	s_waitcnt lgkmcnt(0)
	v_and_b32_e32 v53, 0xffff0000, v72
	v_lshlrev_b32_e32 v54, 16, v73
	v_and_b32_e32 v55, 0xffff0000, v73
	v_lshlrev_b32_e32 v56, 16, v74
	v_and_b32_e32 v57, 0xffff0000, v74
	v_pk_add_f32 v[48:49], v[48:49], v[52:53]
	v_pk_add_f32 v[50:51], v[50:51], v[54:55]
	v_pk_add_f32 v[54:55], v[44:45], v[56:57]
	v_cvt_pk_bf16_f32 v44, v48, v49
	v_mul_f32_e32 v49, v49, v49
	v_fmac_f32_e32 v49, v48, v48
	v_mul_f32_e32 v48, v51, v51
	v_lshlrev_b32_e32 v60, 16, v68
	v_and_b32_e32 v61, 0xffff0000, v68
	v_lshlrev_b32_e32 v62, 16, v69
	v_and_b32_e32 v63, 0xffff0000, v69
	v_fmac_f32_e32 v48, v50, v50
	v_lshlrev_b32_e32 v58, 16, v75
	v_and_b32_e32 v59, 0xffff0000, v75
	v_lshlrev_b32_e32 v64, 16, v70
	v_and_b32_e32 v65, 0xffff0000, v70
	v_add_f32_e32 v48, v49, v48
	v_mul_f32_e32 v49, v55, v55
	v_pk_add_f32 v[42:43], v[42:43], v[62:63]
	v_pk_add_f32 v[40:41], v[40:41], v[60:61]
	v_pk_add_f32 v[52:53], v[46:47], v[58:59]
	v_cvt_pk_bf16_f32 v45, v50, v51
	v_fmac_f32_e32 v49, v54, v54
	v_pk_add_f32 v[50:51], v[36:37], v[64:65]
	v_mul_f32_e32 v36, v41, v41
	v_mul_f32_e32 v37, v43, v43
	v_add_f32_e32 v48, v49, v48
	v_mul_f32_e32 v49, v53, v53
	v_fmac_f32_e32 v36, v40, v40
	v_fmac_f32_e32 v37, v42, v42
	v_lshlrev_b32_e32 v66, 16, v71
	v_and_b32_e32 v67, 0xffff0000, v71
	v_fmac_f32_e32 v49, v52, v52
	v_add_f32_e32 v36, v36, v37
	v_mul_f32_e32 v37, v51, v51
	v_cvt_pk_bf16_f32 v47, v52, v53
	v_add_f32_e32 v52, v49, v48
	v_pk_add_f32 v[48:49], v[38:39], v[66:67]
	v_fmac_f32_e32 v37, v50, v50
	v_add_f32_e32 v36, v37, v36
	v_mul_f32_e32 v37, v49, v49
	v_fmac_f32_e32 v37, v48, v48
	v_add_f32_e32 v36, v37, v36
	v_add_f32_e32 v39, v52, v36
	v_cvt_pk_bf16_f32 v46, v54, v55
	ds_bpermute_b32 v54, v162, v39
	v_lshl_add_u64 v[36:37], s[18:19], 0, v[78:79]
	v_lshl_add_u64 v[52:53], v[150:151], 1, v[36:37]
	v_cvt_pk_bf16_f32 v38, v40, v41
	v_cvt_pk_bf16_f32 v40, v50, v51
	s_waitcnt lgkmcnt(0)
	v_add_f32_e32 v36, v39, v54
	ds_bpermute_b32 v37, v163, v36
	v_cvt_pk_bf16_f32 v39, v42, v43
	v_cvt_pk_bf16_f32 v41, v48, v49
	global_store_dwordx4 v[52:53], v[44:47], off
	global_store_dwordx4 v[52:53], v[38:41], off offset:256
	s_and_saveexec_b64 s[46:47], s[40:41]
	s_cbranch_execz .LBB0_101
	v_lshlrev_b64 v[38:39], 6, v[76:77]
	v_lshl_add_u64 v[38:39], s[86:87], 0, v[38:39]
	v_lshl_add_u64 v[38:39], s[44:45], 2, v[38:39]
	s_lshl_b32 s24, s53, 2
	v_lshl_add_u64 v[38:39], v[38:39], 0, s[24:25]
	s_waitcnt lgkmcnt(0)
	v_add_f32_e32 v36, v36, v37
	global_store_dword v[38:39], v36, off
; __device__ __forceinline__ unsigned pk2(float lo, float hi) { const f32x2_t v = {lo, hi}; const bf16x2_t b = __builtin_convertvector(v, bf16x2_t); return __builtin_bit_cast(unsigned, b); }
; __device__ __forceinline__ float bperm_f(int src_lane, float v) { return __builtin_bit_cast(float, __builtin_amdgcn_ds_bpermute(src_lane << 2, __builtin_bit_cast(int, v))); }
;     __device__ __forceinline__ void operator()(Acc& acc, const Unit& u, int wr, int wc, int fr, int fq) const {
;     ...
;                     for (int bj = 0; bj < 2; ++bj) raw[mm][bj] = *(const u32x4*)(xb + (size_t)(row0 + ai * 128 + (2 * mh + mm) * 16) * DM + col0 + bj * 128);
; #pragma unroll
;                 for (int mm = 0; mm < 2; ++mm)
; #pragma unroll
;                     for (int bj = 0; bj < 2; ++bj) { float t[8]; unpack8(raw[mm][bj], t); b0[mm][bj] = (f32x4){t[0], t[1], t[2], t[3]}; b1[mm][bj] = (f32x4){t[4], t[5], t[6], t[7]}; }
;             }
; #pragma unroll
;             for (int mm = 0; mm < 2; ++mm) { const int m = 2 * mh + mm;
;                 const int row = row0 + ai * 128 + m * 16; float ss = 0.f;
; #pragma unroll
;                 for (int bj = 0; bj < 2; ++bj) { const size_t off = (size_t)row * DM + col0 + bj * 128;
;                     const f32x4 v0 = acc[ai][bj][m][0] + b0[mm][bj], v1 = acc[ai][bj][m][1] + b1[mm][bj];
;                     u32x4 w; w.x = pk2(v0[0], v0[1]); w.y = pk2(v0[2], v0[3]); w.z = pk2(v1[0], v1[1]); w.w = pk2(v1[2], v1[3]);
;                     *(u32x4*)(xb + off) = w;
;                     ss += (v0[0] * v0[0] + v0[1] * v0[1]) + (v0[2] * v0[2] + v0[3] * v0[3]) + (v1[0] * v1[0] + v1[1] * v1[1]) + (v1[2] * v1[2] + v1[3] * v1[3]); }
;                 ss += bperm_f(ln ^ 16, ss); ss += bperm_f(ln ^ 32, ss);
;                 if (fq == 0) ssq[(size_t)row * 16 + u.pn * 4 + wc] = ss;
.LBB0_101:
	s_or_b64 exec, exec, s[46:47]
	v_add_u32_e32 v48, 0xa0, v152
	v_ashrrev_i32_e32 v49, 31, v48
	v_lshlrev_b64 v[58:59], 11, v[48:49]
	s_waitcnt lgkmcnt(0)
	v_lshl_add_u64 v[36:37], v[154:155], 0, v[58:59]
	s_waitcnt vmcnt(12)
	v_mov_b64_e32 v[50:51], v[222:223]
	v_mov_b64_e32 v[52:53], v[224:225]
	v_mov_b64_e32 v[54:55], v[226:227]
	v_mov_b64_e32 v[56:57], v[228:229]
	v_add_u32_e32 v44, 0xb0, v152
	v_ashrrev_i32_e32 v45, 31, v44
	v_lshlrev_b64 v[46:47], 11, v[44:45]
	v_lshl_add_u64 v[36:37], v[154:155], 0, v[46:47]
	v_mov_b64_e32 v[40:41], v[230:231]
	v_mov_b64_e32 v[42:43], v[232:233]
	s_nop 0
	v_mov_b64_e32 v[36:37], v[234:235]
	v_mov_b64_e32 v[38:39], v[236:237]
	s_waitcnt lgkmcnt(0)
	v_lshlrev_b32_e32 v60, 16, v50
	v_and_b32_e32 v61, 0xffff0000, v50
	v_lshlrev_b32_e32 v50, 16, v51
	v_and_b32_e32 v51, 0xffff0000, v51
	v_lshlrev_b32_e32 v64, 16, v54
	v_and_b32_e32 v65, 0xffff0000, v54
	v_lshlrev_b32_e32 v54, 16, v55
	v_and_b32_e32 v55, 0xffff0000, v55
	v_lshlrev_b32_e32 v62, 16, v52
	v_and_b32_e32 v63, 0xffff0000, v52
	v_lshlrev_b32_e32 v52, 16, v53
	v_and_b32_e32 v53, 0xffff0000, v53
	v_lshlrev_b32_e32 v66, 16, v56
	v_and_b32_e32 v67, 0xffff0000, v56
	v_pk_add_f32 v[34:35], v[34:35], v[50:51]
	v_pk_add_f32 v[32:33], v[32:33], v[60:61]
	v_pk_add_f32 v[26:27], v[26:27], v[54:55]
	v_pk_add_f32 v[24:25], v[24:25], v[64:65]
	v_lshlrev_b32_e32 v56, 16, v57
	v_and_b32_e32 v57, 0xffff0000, v57
	v_pk_add_f32 v[30:31], v[30:31], v[52:53]
	v_pk_add_f32 v[28:29], v[28:29], v[62:63]
	v_pk_add_f32 v[52:53], v[20:21], v[66:67]
	v_cvt_pk_bf16_f32 v20, v32, v33
	v_cvt_pk_bf16_f32 v21, v34, v35
	v_mul_f32_e32 v33, v33, v33
	v_mul_f32_e32 v35, v35, v35
	v_mul_f32_e32 v54, v25, v25
	v_mul_f32_e32 v55, v27, v27
	v_pk_add_f32 v[50:51], v[22:23], v[56:57]
	v_cvt_pk_bf16_f32 v22, v28, v29
	v_cvt_pk_bf16_f32 v23, v30, v31
	v_mul_f32_e32 v29, v29, v29
	v_mul_f32_e32 v31, v31, v31
	v_mul_f32_e32 v56, v53, v53
	v_fmac_f32_e32 v33, v32, v32
	v_fmac_f32_e32 v35, v34, v34
	v_fmac_f32_e32 v54, v24, v24
	v_fmac_f32_e32 v55, v26, v26
	v_mul_f32_e32 v57, v51, v51
	v_fmac_f32_e32 v29, v28, v28
	v_fmac_f32_e32 v31, v30, v30
	v_fmac_f32_e32 v56, v52, v52
	v_add_f32_e32 v28, v33, v35
	v_add_f32_e32 v30, v54, v55
	v_fmac_f32_e32 v57, v50, v50
	v_add_f32_e32 v28, v29, v28
	v_add_f32_e32 v29, v56, v30
	v_add_f32_e32 v28, v31, v28
	v_add_f32_e32 v29, v57, v29
	v_add_f32_e32 v30, v28, v29
	ds_bpermute_b32 v31, v162, v30
	v_lshl_add_u64 v[28:29], s[18:19], 0, v[58:59]
	v_lshl_add_u64 v[28:29], v[150:151], 1, v[28:29]
	global_store_dwordx4 v[28:29], v[20:23], off
	s_waitcnt lgkmcnt(0)
	s_nop 0
	v_add_f32_e32 v20, v30, v31
	ds_bpermute_b32 v21, v163, v20
	v_cvt_pk_bf16_f32 v22, v24, v25
	v_cvt_pk_bf16_f32 v23, v26, v27
	v_cvt_pk_bf16_f32 v24, v52, v53
	v_cvt_pk_bf16_f32 v25, v50, v51
	global_store_dwordx4 v[28:29], v[22:25], off offset:256
	s_and_saveexec_b64 s[46:47], s[40:41]
	s_cbranch_execz .LBB0_103
	v_lshlrev_b64 v[22:23], 6, v[48:49]
	v_lshl_add_u64 v[22:23], s[86:87], 0, v[22:23]
	v_lshl_add_u64 v[22:23], s[44:45], 2, v[22:23]
	s_lshl_b32 s24, s53, 2
	v_lshl_add_u64 v[22:23], v[22:23], 0, s[24:25]
	s_waitcnt lgkmcnt(0)
	v_add_f32_e32 v20, v20, v21
	global_store_dword v[22:23], v20, off
.LBB0_103:
	s_or_b64 exec, exec, s[46:47]
	v_lshlrev_b32_e32 v20, 16, v40
	s_waitcnt lgkmcnt(0)
	v_and_b32_e32 v21, 0xffff0000, v40
	v_lshlrev_b32_e32 v22, 16, v41
	v_and_b32_e32 v23, 0xffff0000, v41
	v_lshlrev_b32_e32 v24, 16, v42
	v_and_b32_e32 v25, 0xffff0000, v42
	v_pk_add_f32 v[16:17], v[16:17], v[20:21]
	v_pk_add_f32 v[18:19], v[18:19], v[22:23]
	v_pk_add_f32 v[22:23], v[12:13], v[24:25]
	v_cvt_pk_bf16_f32 v12, v16, v17
	v_mul_f32_e32 v17, v17, v17
	v_fmac_f32_e32 v17, v16, v16
	v_mul_f32_e32 v16, v19, v19
	v_lshlrev_b32_e32 v28, 16, v36
	v_and_b32_e32 v29, 0xffff0000, v36
	v_lshlrev_b32_e32 v30, 16, v37
	v_and_b32_e32 v31, 0xffff0000, v37
	v_fmac_f32_e32 v16, v18, v18
	v_lshlrev_b32_e32 v26, 16, v43
	v_and_b32_e32 v27, 0xffff0000, v43
	v_lshlrev_b32_e32 v32, 16, v38
	v_and_b32_e32 v33, 0xffff0000, v38
	v_add_f32_e32 v16, v17, v16
	v_mul_f32_e32 v17, v23, v23
	v_pk_add_f32 v[10:11], v[10:11], v[30:31]
	v_pk_add_f32 v[8:9], v[8:9], v[28:29]
	v_pk_add_f32 v[20:21], v[14:15], v[26:27]
	v_cvt_pk_bf16_f32 v13, v18, v19
	v_fmac_f32_e32 v17, v22, v22
	v_pk_add_f32 v[18:19], v[4:5], v[32:33]
	v_mul_f32_e32 v4, v9, v9
	v_mul_f32_e32 v5, v11, v11
	v_add_f32_e32 v16, v17, v16
	v_mul_f32_e32 v17, v21, v21
	v_fmac_f32_e32 v4, v8, v8
	v_fmac_f32_e32 v5, v10, v10
	v_lshlrev_b32_e32 v34, 16, v39
	v_and_b32_e32 v35, 0xffff0000, v39
	v_fmac_f32_e32 v17, v20, v20
	v_add_f32_e32 v4, v4, v5
	v_mul_f32_e32 v5, v19, v19
	v_cvt_pk_bf16_f32 v15, v20, v21
	v_add_f32_e32 v20, v17, v16
	v_pk_add_f32 v[16:17], v[6:7], v[34:35]
	v_fmac_f32_e32 v5, v18, v18
	v_add_f32_e32 v4, v5, v4
	v_mul_f32_e32 v5, v17, v17
	v_fmac_f32_e32 v5, v16, v16
	v_add_f32_e32 v4, v5, v4
	v_add_f32_e32 v7, v20, v4
	v_cvt_pk_bf16_f32 v14, v22, v23
	ds_bpermute_b32 v22, v162, v7
	v_lshl_add_u64 v[4:5], s[18:19], 0, v[46:47]
	v_lshl_add_u64 v[20:21], v[150:151], 1, v[4:5]
	v_cvt_pk_bf16_f32 v6, v8, v9
	v_cvt_pk_bf16_f32 v8, v18, v19
	s_waitcnt lgkmcnt(0)
	v_add_f32_e32 v4, v7, v22
	ds_bpermute_b32 v5, v163, v4
	v_cvt_pk_bf16_f32 v7, v10, v11
	v_cvt_pk_bf16_f32 v9, v16, v17
	global_store_dwordx4 v[20:21], v[12:15], off
	global_store_dwordx4 v[20:21], v[6:9], off offset:256
	s_and_saveexec_b64 s[46:47], s[40:41]
	s_cbranch_execz .LBB0_105
	v_lshlrev_b64 v[6:7], 6, v[44:45]
	v_lshl_add_u64 v[6:7], s[86:87], 0, v[6:7]
	v_lshl_add_u64 v[6:7], s[44:45], 2, v[6:7]
	s_lshl_b32 s24, s53, 2
	v_lshl_add_u64 v[6:7], v[6:7], 0, s[24:25]
	s_waitcnt lgkmcnt(0)
	v_add_f32_e32 v4, v4, v5
	global_store_dword v[6:7], v4, off
